# sub-phase 2 work queue: the eight long dn_scan chains are taken by workgroups 0-7 (distinct XCDs) instead of whichever workgroups arrive first, so two chains never share a CU
# speedup vs baseline: 1.0071x; 1.0071x over previous
; __global__ void __launch_bounds__(256, 2) mega(P p, int ph_lo, int ph_hi) {
;     ...
;   for (int layer = 0; layer < 2; ++layer) {
; #pragma unroll
;     for (int sub = 0; sub < 10; ++sub) {
;       run_phase(p, 1 + layer * 10 + sub, smem, &s_item);
;       grid.sync();
;     }
.LBB0_100:
	s_or_b64 exec, exec, s[0:1]
	s_mov_b32 s2, 1
	s_nop 0
	v_writelane_b32 v255, s2, 48
	v_readlane_b32 s0, v254, 12
	s_add_i32 s0, s0, 1
	s_cmp_eq_u32 s0, 10
	v_writelane_b32 v254, s0, 12
	s_barrier
	s_cbranch_scc1 .LBB0_97

; __device__ __forceinline__ void run_phase(const P& pp, int ph, char* smem, int* s_item) {
;     ...
;   while (true) {
;     if (threadIdx.x == 0) *s_item = atomicAdd(ctr, 1);
;     __syncthreads();
;     const int it = *s_item;
;     __syncthreads();
;     if (it >= total) break;
.LBB0_273:
	s_mov_b64 s[0:1], exec
	v_readlane_b32 s2, v252, 45
	v_readlane_b32 s3, v252, 46
	s_and_b64 s[2:3], s[0:1], s[2:3]
	s_mov_b64 exec, s[2:3]
	s_cbranch_execz .LBB0_277
	s_mov_b64 s[4:5], exec
	s_waitcnt vmcnt(51)
	v_mbcnt_lo_u32_b32 v0, s4, 0
	v_mbcnt_hi_u32_b32 v0, s5, v0
	v_cmp_eq_u32_e32 vcc, 0, v0
	s_and_saveexec_b64 s[2:3], vcc
	s_cbranch_execz .LBB0_276
	s_bcnt1_i32_b64 s4, s[4:5]
	v_mov_b32_e32 v1, s4
	v_readlane_b32 s4, v254, 16
	v_readlane_b32 s5, v254, 17
	v_readlane_b32 vcc_lo, v254, 12
	v_readlane_b32 vcc_hi, v255, 48
	s_nop 0
	s_cmp_lg_u32 vcc_lo, 2
	s_cbranch_scc1 .Lq_atomic
	s_cmp_lg_u32 vcc_hi, 1
	s_cbranch_scc1 .Lq_atomic8
	v_readlane_b32 vcc_hi, v252, 2
	s_nop 0
	s_cmp_ge_u32 vcc_hi, 32
	s_cbranch_scc1 .Lq_atomic8
	s_lshr_b32 vcc_hi, vcc_hi, 2
	s_nop 0
	v_mov_b32_e32 v1, vcc_hi
	s_branch .Lq_done
.Lq_atomic8:
	s_nop 2
	global_atomic_add v1, v177, v1, s[4:5] sc0
	s_waitcnt vmcnt(0)
	v_add_u32_e32 v1, 8, v1
	s_branch .Lq_done
.Lq_atomic:
	s_nop 2
	global_atomic_add v1, v177, v1, s[4:5] sc0
.Lq_done:
	s_mov_b32 vcc_lo, 0
	s_nop 0
	v_writelane_b32 v255, vcc_lo, 48
